# v24: v19 + guarded XCD-local grid barriers (all three per-layer barriers): when every blockIdx%8 class sits on one XCC (checked at run time via per-class atomic max/min before the first global barrier
# speedup vs baseline: 1.0411x; 1.0411x over previous
; #define LAS __attribute__((address_space(3)))
; __device__ __forceinline__ unsigned xb_add(unsigned* p, unsigned v) { return __hip_atomic_fetch_add(p, v, __ATOMIC_RELAXED, __HIP_MEMORY_SCOPE_AGENT); }
; __device__ __forceinline__ unsigned xb_xcc_id() { return (unsigned)__builtin_amdgcn_s_getreg((3 << 11) | 20) & 0xFu; }
; __device__ __forceinline__ XcdBarrier xcd_barrier_post(unsigned* bar, volatile LAS unsigned* st) {
;     XcdBarrier b; b.bar = bar; b.x = xb_xcc_id(); b.st = st;
;     if (threadIdx.x == 0) (void)xb_add(&bar[XB_XCNT(b.x)], 1u);
;     return b;
; }
; __global__ void __launch_bounds__(512, 2) mega_fwd(Params p) {
;     ...
;     volatile LAS unsigned* misc = (volatile LAS unsigned*)(lds + MISC_OFF);
;     if (threadIdx.x < 2) misc[threadIdx.x] = 0u;
;     __syncthreads();
;     const XcdBarrier bar = xcd_barrier_post((unsigned*)(p.ws + WS_CTL), misc);
_Z8mega_fwd6Params:
	s_load_dwordx8 s[72:79], s[0:1], 0x40
	s_load_dword s33, s[0:1], 0x78
	s_load_dwordx4 s[92:95], s[0:1], 0x60
	s_load_dwordx2 s[80:81], s[0:1], 0x70
	s_add_u32 s8, s0, 0x70
	v_and_b32_e32 v196, 0x3ff, v0
	s_mov_b32 s68, s2
	s_addc_u32 s9, s1, 0
	v_cmp_gt_u32_e32 vcc, 2, v196
	s_and_saveexec_b64 s[2:3], vcc
	v_lshl_add_u32 v1, v196, 2, 0
	v_add_u32_e32 v1, 0x25fc0, v1
	v_mov_b32_e32 v2, 0
	ds_write_b32 v1, v2
	s_or_b64 exec, exec, s[2:3]
	s_load_dwordx16 s[12:27], s[0:1], 0x0
	s_waitcnt lgkmcnt(0)
	s_barrier
	s_add_u32 s2, s94, 0x6980000
	v_writelane_b32 v252, s12, 0
	s_getreg_b32 s0, hwreg(HW_REG_XCC_ID, 0, 4)
	s_addc_u32 s3, s95, 0
	v_writelane_b32 v252, s13, 1
	v_writelane_b32 v252, s14, 2
	v_writelane_b32 v252, s15, 3
	v_writelane_b32 v252, s16, 4
	v_writelane_b32 v252, s17, 5
	v_writelane_b32 v252, s18, 6
	v_writelane_b32 v252, s19, 7
	v_writelane_b32 v252, s20, 8
	v_writelane_b32 v252, s21, 9
	v_writelane_b32 v252, s22, 10
	v_writelane_b32 v252, s23, 11
	v_writelane_b32 v252, s24, 12
	v_writelane_b32 v252, s25, 13
	v_writelane_b32 v252, s26, 14
	v_writelane_b32 v252, s27, 15
	s_and_b32 s48, s0, 15
	s_mov_b32 s7, 0
	v_cmp_eq_u32_e64 s[70:71], 0, v196
	s_and_saveexec_b64 s[0:1], s[70:71]
	s_cbranch_execz .LBB0_5
	s_mov_b64 s[4:5], exec
	v_mbcnt_lo_u32_b32 v1, s4, 0
	v_mbcnt_hi_u32_b32 v1, s5, v1
	v_cmp_eq_u32_e32 vcc, 0, v1
	s_and_b64 s[10:11], exec, vcc
	s_mov_b64 exec, s[10:11]
	s_cbranch_execz .LBB0_5
	s_lshl_b32 s6, s48, 8
	s_bcnt1_i32_b64 s4, s[4:5]
	v_mov_b32_e32 v1, s6
	v_mov_b32_e32 v2, s4
	global_atomic_add v1, v2, s[2:3] offset:1024
	s_and_b32 s6, s68, 7
	s_lshl_b32 s6, s6, 2
	s_add_i32 s6, s6, 0x3800
	v_mov_b32_e32 v1, s6
	s_add_i32 s4, s48, 1
	v_mov_b32_e32 v2, s4
	global_atomic_umax v1, v2, s[2:3]
	s_sub_i32 s4, 16, s48
	v_mov_b32_e32 v2, s4
	global_atomic_umax v1, v2, s[2:3] offset:32

; __device__ __forceinline__ unsigned xb_ld(unsigned* p)              { return __hip_atomic_load(p, __ATOMIC_RELAXED, __HIP_MEMORY_SCOPE_AGENT); }
; __device__ __forceinline__ unsigned xb_add(unsigned* p, unsigned v) { return __hip_atomic_fetch_add(p, v, __ATOMIC_RELAXED, __HIP_MEMORY_SCOPE_AGENT); }
; __device__ __forceinline__ void xcd_barrier_complete(unsigned* bar, unsigned x, unsigned& nloc, unsigned& nx) {
;     const unsigned G = gridDim.x * gridDim.y * gridDim.z;
;     unsigned sum, cnt, mine, sp = 0u;
;     for (;;) {
;         sum = 0u; cnt = 0u; mine = 0u;
; #pragma unroll
;         for (unsigned j = 0; j < 16; ++j) { const unsigned c = xb_ld(&bar[XB_XCNT(j)]); sum += c; cnt += (c > 0u) ? 1u : 0u; mine = (j == x) ? c : mine; }
;         if (sum == G) break;
;         __builtin_amdgcn_s_sleep(1);
;         if ((++sp & 255u) == 0u) { if (xb_ld(&bar[XB_TMO])) break; if (sp > XB_SPIN_CAP) { atomicAdd(&bar[XB_TMO], 1u); break; } }
;     }
;     nloc = mine > 0u ? mine : 1u; nx = cnt > 0u ? cnt : 1u;
; }
; __device__ __forceinline__ void xcd_barrier(const XcdBarrier& b) {
;     asm volatile("s_waitcnt vmcnt(0)" ::: "memory");
;     __syncthreads();
;     if (threadIdx.x == 0) {
;         unsigned* bar = b.bar;
;         __builtin_amdgcn_s_waitcnt(0);
;         unsigned nloc = b.st[0], nx = b.st[1];
;         if (nloc == 0u) { xcd_barrier_complete(bar, b.x, nloc, nx); b.st[0] = nloc; b.st[1] = nx; }
;         const unsigned old = xb_add(&bar[XB_XSUB(b.x)], 1u);
;         const unsigned gen = old / nloc;
;         if (old + 1u == (gen + 1u) * nloc) {
;             __builtin_amdgcn_fence(__ATOMIC_RELEASE, "agent");
;             asm volatile("s_waitcnt vmcnt(0)" ::: "memory");
;             const unsigned og = xb_add(&bar[XB_TOP], 1u);
;             const unsigned tg = og / nx;
;             if (og + 1u == (tg + 1u) * nx) xb_add(&bar[XB_TOPGEN], 1u);
;             else XB_SPIN(xb_ld(&bar[XB_TOPGEN]) == tg, bar);
;             __builtin_amdgcn_fence(__ATOMIC_ACQUIRE, "agent");
;             xb_add(&bar[XB_XGEN(b.x)], 1u);
;             asm volatile("s_waitcnt vmcnt(0)" ::: "memory");
;         } else {
;             XB_SPIN(xb_ld(&bar[XB_XGEN(b.x)]) == gen, bar);
;             __builtin_amdgcn_fence(__ATOMIC_ACQUIRE, "agent");
;             asm volatile("s_waitcnt vmcnt(0)" ::: "memory");
;         }
.LBB0_277:
	s_add_u32 s0, s94, 0x6a00000
	s_addc_u32 s1, s95, 0
	s_add_u32 s6, s94, 0x12a00000
	s_addc_u32 s7, s95, 0
	s_add_u32 s8, s94, 0x15a00000
	s_addc_u32 s9, s95, 0
	v_writelane_b32 v252, s51, 21
	s_add_u32 s10, s94, 0x18a00000
	v_writelane_b32 v252, s0, 22
	s_addc_u32 s11, s95, 0
	s_ashr_i32 s91, s68, 31
	v_writelane_b32 v252, s1, 23
	s_lshr_b32 s0, s91, 29
	s_add_i32 s0, s68, s0
	s_ashr_i32 s12, s0, 3
	s_and_b32 s0, s0, -8
	s_sub_i32 s13, s68, s0
	s_ashr_i32 s0, s80, 31
	v_writelane_b32 v252, s0, 24
	s_add_u32 s0, s94, 0x6980200
	s_addc_u32 s1, s95, 0
	v_writelane_b32 v252, s0, 25
	s_mov_b32 s84, 0x3f803f80
	v_mov_b32_e32 v113, 0
	v_writelane_b32 v252, s1, 26
	s_add_u32 s0, s94, 0x6980400
	s_addc_u32 s1, s95, 0
	v_writelane_b32 v252, s0, 27
	v_mov_b32_e32 v198, 0x358637bd
	v_mov_b32_e32 v199, 1
	v_writelane_b32 v252, s1, 28
	s_add_u32 s0, s94, 0x6980500
	s_addc_u32 s1, s95, 0
	v_writelane_b32 v252, s0, 29
	s_mov_b32 s85, s84
	s_mov_b32 s86, s84
	v_writelane_b32 v252, s1, 30
	s_add_u32 s0, s94, 0x6980600
	s_addc_u32 s1, s95, 0
	v_writelane_b32 v252, s0, 31
	s_mov_b32 s87, s84
	v_mov_b32_e32 v200, 0xffffff60
	v_writelane_b32 v252, s1, 32
	s_add_u32 s0, s94, 0x6980700
	s_addc_u32 s1, s95, 0
	v_writelane_b32 v252, s0, 33
	v_mov_b32_e32 v201, 0x10000
	v_mov_b64_e32 v[186:187], 0x200
	v_writelane_b32 v252, s1, 34
	s_add_u32 s0, s94, 0x6980800
	s_addc_u32 s1, s95, 0
	v_writelane_b32 v252, s0, 35
	v_mov_b64_e32 v[188:189], 0x1ff
	s_nop 0
	v_writelane_b32 v252, s1, 36
	s_add_u32 s0, s94, 0x6980900
	s_addc_u32 s1, s95, 0
	v_writelane_b32 v252, s0, 37
	s_nop 1
	v_writelane_b32 v252, s1, 38
	s_add_u32 s0, s94, 0x6980a00
	s_addc_u32 s1, s95, 0
	v_writelane_b32 v252, s0, 39
	s_nop 1
	v_writelane_b32 v252, s1, 40
	s_add_u32 s0, s94, 0x6980b00
	s_addc_u32 s1, s95, 0
	v_writelane_b32 v252, s0, 41
	s_nop 1
	v_writelane_b32 v252, s1, 42
	s_add_u32 s0, s94, 0x6980c00
	s_addc_u32 s1, s95, 0
	v_writelane_b32 v252, s0, 43
	s_nop 1
	v_writelane_b32 v252, s1, 44
	s_add_u32 s0, s94, 0x6980d00
	s_addc_u32 s1, s95, 0
	v_writelane_b32 v252, s0, 45
	s_nop 1
	v_writelane_b32 v252, s1, 46
	s_add_u32 s0, s94, 0x6980e00
	s_addc_u32 s1, s95, 0
	v_writelane_b32 v252, s0, 47
	s_nop 1
	v_writelane_b32 v252, s1, 48
	s_add_u32 s0, s94, 0x6980f00
	s_addc_u32 s1, s95, 0
	v_writelane_b32 v252, s0, 49
	s_nop 1
	v_writelane_b32 v252, s1, 50
	s_add_u32 s0, s94, 0x6981000
	s_addc_u32 s1, s95, 0
	v_writelane_b32 v252, s0, 51
	s_nop 1
	v_writelane_b32 v252, s1, 52
	s_add_u32 s0, s94, 0x6981100
	s_addc_u32 s1, s95, 0
	v_writelane_b32 v252, s0, 53
	s_nop 1
	v_writelane_b32 v252, s1, 54
	s_add_u32 s0, s94, 0x6981200
	s_addc_u32 s1, s95, 0
	v_writelane_b32 v252, s0, 55
	s_nop 1
	v_writelane_b32 v252, s1, 56
	s_add_u32 s0, s94, 0x6981300
	s_addc_u32 s1, s95, 0
	v_writelane_b32 v252, s0, 57
	s_cmp_eq_u32 s48, 15
	s_nop 0
	v_writelane_b32 v252, s1, 58
	s_cselect_b64 s[0:1], -1, 0
	v_writelane_b32 v252, s0, 59
	s_cmp_eq_u32 s48, 14
	s_nop 0
	v_writelane_b32 v252, s1, 60
	s_cselect_b64 s[0:1], -1, 0
	v_writelane_b32 v252, s0, 61
	s_cmp_eq_u32 s48, 13
	s_nop 0
	v_writelane_b32 v252, s1, 62
	s_cselect_b64 s[0:1], -1, 0
	v_writelane_b32 v252, s0, 63
	s_cmp_eq_u32 s48, 12
	s_nop 0
	v_writelane_b32 v253, s1, 0
	s_cselect_b64 s[0:1], -1, 0
	v_writelane_b32 v253, s0, 1
	s_cmp_eq_u32 s48, 11
	s_nop 0
	v_writelane_b32 v253, s1, 2
	s_cselect_b64 s[0:1], -1, 0
	v_writelane_b32 v253, s0, 3
	s_cmp_eq_u32 s48, 10
	s_nop 0
	v_writelane_b32 v253, s1, 4
	s_cselect_b64 s[0:1], -1, 0
	v_writelane_b32 v253, s0, 5
	s_cmp_eq_u32 s48, 9
	s_nop 0
	v_writelane_b32 v253, s1, 6
	s_cselect_b64 s[0:1], -1, 0
	v_writelane_b32 v253, s0, 7
	s_cmp_eq_u32 s48, 8
	s_nop 0
	v_writelane_b32 v253, s1, 8
	s_cselect_b64 s[0:1], -1, 0
	v_writelane_b32 v253, s0, 9
	s_cmp_eq_u32 s48, 7
	s_nop 0
	v_writelane_b32 v253, s1, 10
	s_cselect_b64 s[0:1], -1, 0
	v_writelane_b32 v253, s0, 11
	s_cmp_eq_u32 s48, 6
	s_nop 0
	v_writelane_b32 v253, s1, 12
	s_cselect_b64 s[0:1], -1, 0
	v_writelane_b32 v253, s0, 13
	s_cmp_eq_u32 s48, 5
	s_nop 0
	v_writelane_b32 v253, s1, 14
	s_cselect_b64 s[0:1], -1, 0
	v_writelane_b32 v253, s0, 15
	s_cmp_eq_u32 s48, 4
	s_nop 0
	v_writelane_b32 v253, s1, 16
	s_cselect_b64 s[0:1], -1, 0
	v_writelane_b32 v253, s0, 17
	s_cmp_eq_u32 s48, 3
	s_nop 0
	v_writelane_b32 v253, s1, 18
	s_cselect_b64 s[0:1], -1, 0
	v_writelane_b32 v253, s0, 19
	s_cmp_eq_u32 s48, 2
	s_nop 0
	v_writelane_b32 v253, s1, 20
	s_cselect_b64 s[0:1], -1, 0
	v_writelane_b32 v253, s0, 21
	s_cmp_eq_u32 s48, 1
	s_nop 0
	v_writelane_b32 v253, s1, 22
	s_cselect_b64 s[0:1], -1, 0
	v_writelane_b32 v253, s0, 23
	s_cmp_eq_u32 s48, 0
	s_nop 0
	v_writelane_b32 v253, s1, 24
	s_cselect_b64 s[0:1], -1, 0
	v_writelane_b32 v253, s0, 25
	s_nop 1
	v_writelane_b32 v253, s1, 26
	s_lshl_b32 s0, s48, 8
	s_add_u32 s0, s2, s0
	s_addc_u32 s1, s3, 0
	s_add_u32 s2, s0, 0x1400
	s_addc_u32 s3, s1, 0
	v_writelane_b32 v253, s2, 27
	s_add_u32 s0, s0, 0x2400
	s_addc_u32 s1, s1, 0
	v_writelane_b32 v253, s3, 28
	v_writelane_b32 v253, s0, 29
	s_nop 1
	v_writelane_b32 v253, s1, 30
	s_add_u32 s0, s94, 0x6983400
	s_addc_u32 s1, s95, 0
	v_writelane_b32 v253, s0, 31
	s_nop 1
	v_writelane_b32 v253, s1, 32
	s_add_u32 s0, s94, 0x6983500
	s_addc_u32 s1, s95, 0
	v_writelane_b32 v253, s0, 33
	s_cmpk_lt_i32 s68, 0x400
	s_nop 0
	v_writelane_b32 v253, s1, 34
	s_cselect_b64 s[0:1], -1, 0
	v_writelane_b32 v253, s0, 35
	s_cmpk_lg_i32 s80, 0x100
	s_nop 0
	v_writelane_b32 v253, s1, 36
	s_cselect_b64 s[0:1], -1, 0
	v_writelane_b32 v253, s0, 37
	s_nop 1
	v_writelane_b32 v253, s1, 38
	s_lshl_b32 s0, s68, 7
; #define LAS __attribute__((address_space(3)))
; __device__ __forceinline__ unsigned xb_ld(unsigned* p)              { return __hip_atomic_load(p, __ATOMIC_RELAXED, __HIP_MEMORY_SCOPE_AGENT); }
; __device__ __forceinline__ unsigned xb_add(unsigned* p, unsigned v) { return __hip_atomic_fetch_add(p, v, __ATOMIC_RELAXED, __HIP_MEMORY_SCOPE_AGENT); }
; __device__ __forceinline__ unsigned xb_xcc_id() { return (unsigned)__builtin_amdgcn_s_getreg((3 << 11) | 20) & 0xFu; }
; __device__ __forceinline__ XcdBarrier xcd_barrier_post(unsigned* bar, volatile LAS unsigned* st) {
;     XcdBarrier b; b.bar = bar; b.x = xb_xcc_id(); b.st = st;
;     if (threadIdx.x == 0) (void)xb_add(&bar[XB_XCNT(b.x)], 1u);
;     return b;
; }
; __device__ __forceinline__ void xcd_barrier_complete(unsigned* bar, unsigned x, unsigned& nloc, unsigned& nx) {
;     const unsigned G = gridDim.x * gridDim.y * gridDim.z;
;     unsigned sum, cnt, mine, sp = 0u;
;     for (;;) {
;         sum = 0u; cnt = 0u; mine = 0u;
; #pragma unroll
;         for (unsigned j = 0; j < 16; ++j) { const unsigned c = xb_ld(&bar[XB_XCNT(j)]); sum += c; cnt += (c > 0u) ? 1u : 0u; mine = (j == x) ? c : mine; }
;         if (sum == G) break;
;         __builtin_amdgcn_s_sleep(1);
;         if ((++sp & 255u) == 0u) { if (xb_ld(&bar[XB_TMO])) break; if (sp > XB_SPIN_CAP) { atomicAdd(&bar[XB_TMO], 1u); break; } }
;     }
;     nloc = mine > 0u ? mine : 1u; nx = cnt > 0u ? cnt : 1u;
; }
; __device__ __forceinline__ void xcd_barrier(const XcdBarrier& b) {
;     asm volatile("s_waitcnt vmcnt(0)" ::: "memory");
;     __syncthreads();
;     if (threadIdx.x == 0) {
;         unsigned* bar = b.bar;
;         __builtin_amdgcn_s_waitcnt(0);
;         unsigned nloc = b.st[0], nx = b.st[1];
;         if (nloc == 0u) { xcd_barrier_complete(bar, b.x, nloc, nx); b.st[0] = nloc; b.st[1] = nx; }
	s_lshr_b32 s1, s68, 3
	s_and_b32 s0, s0, 0x380
	s_and_b32 s1, s1, 0x1fffffe0
	s_add_i32 s0, s0, s1
	s_bfe_u32 s1, s68, 0x50003
	s_or_b32 s2, s0, s1
	s_cmpk_eq_i32 s80, 0x100
	s_cselect_b64 s[0:1], -1, 0
	v_writelane_b32 v253, s0, 39
	s_nop 1
	v_writelane_b32 v253, s1, 40
	s_and_b64 s[0:1], s[0:1], exec
	s_cselect_b32 s4, s2, s68
	s_ashr_i32 s5, s4, 31
	s_lshr_b32 s0, s5, 27
	s_add_i32 s0, s4, s0
	s_ashr_i32 s1, s0, 5
	s_lshr_b32 s2, s1, 30
	s_add_i32 s2, s1, s2
	s_and_b32 s2, s2, 0x3fffffc
	s_sub_i32 s2, s1, s2
	s_and_b32 s0, s0, 0x1ffffe0
	s_lshr_b32 s1, s5, 25
	s_sub_i32 s0, s4, s0
	s_add_i32 s1, s4, s1
	s_lshl_b32 s2, s2, 6
	s_lshl_b32 s14, s0, 7
	s_ashr_i32 s0, s1, 7
	s_ashr_i32 s3, s2, 31
	s_ashr_i32 s1, s0, 31
	s_lshl_b64 s[2:3], s[2:3], 1
	s_add_u32 s16, s6, s2
	s_addc_u32 s17, s7, s3
	v_writelane_b32 v253, s16, 41
	s_add_u32 s2, s8, s2
	s_addc_u32 s3, s9, s3
	v_writelane_b32 v253, s17, 42
	v_writelane_b32 v253, s2, 43
	s_nop 1
	v_writelane_b32 v253, s3, 44
	s_add_i32 s2, s14, 0xffffff80
	v_writelane_b32 v253, s2, 45
	s_sub_i32 s2, s14, 64
	v_writelane_b32 v253, s2, 46
	s_or_b32 s2, s14, 64
	v_writelane_b32 v253, s2, 47
	v_writelane_b32 v253, s14, 48
	s_add_i32 s2, s14, 0x80
	v_writelane_b32 v253, s2, 49
	s_lshl_b64 s[2:3], s[0:1], 20
	v_writelane_b32 v253, s2, 50
	s_nop 1
	v_writelane_b32 v253, s3, 51
	s_add_u32 s2, s94, 0x13a00000
	v_writelane_b32 v253, s2, 52
	s_addc_u32 s2, s95, 0
	v_writelane_b32 v253, s2, 53
	s_add_u32 s2, s94, 0x16a00000
	v_writelane_b32 v253, s2, 54
	s_addc_u32 s2, s95, 0
	v_writelane_b32 v253, s2, 55
	s_lshr_b32 s2, s5, 26
	s_add_i32 s2, s4, s2
	s_and_b32 s3, s2, 0x3ffffc0
	s_sub_i32 s3, s4, s3
	s_ashr_i32 s4, s2, 6
	s_lshr_b32 s2, s2, 31
	s_add_i32 s2, s4, s2
	s_and_b32 s2, s2, 0x3fffffe
	s_sub_i32 s2, s4, s2
	s_lshl_b32 s2, s2, 6
	s_lshl_b32 s4, s3, 6
	s_ashr_i32 s3, s2, 31
	s_lshl_b64 s[2:3], s[2:3], 1
	s_add_u32 s14, s6, s2
	v_writelane_b32 v253, s6, 56
	s_addc_u32 s15, s7, s3
	s_add_u32 s2, s8, s2
	v_writelane_b32 v253, s7, 57
	v_writelane_b32 v253, s14, 58
	s_nop 1
	v_writelane_b32 v253, s15, 59
	v_writelane_b32 v253, s8, 60
	s_addc_u32 s3, s9, s3
	s_lshl_b64 s[0:1], s[0:1], 19
	v_writelane_b32 v251, s0, 0
	v_writelane_b32 v253, s9, 61
	v_writelane_b32 v253, s2, 62
	v_writelane_b32 v251, s1, 1
	s_add_i32 s0, s4, 0xffffff80
	v_writelane_b32 v251, s0, 2
	v_writelane_b32 v251, s4, 3
	s_sub_i32 s0, s4, 64
	v_writelane_b32 v251, s0, 4
	s_add_u32 s0, s94, 0x1ca00000
	s_addc_u32 s1, s95, 0
	v_writelane_b32 v251, s0, 5
	s_cmpk_lt_i32 s68, 0x200
	v_writelane_b32 v253, s3, 63
	v_writelane_b32 v251, s1, 6
	s_cselect_b64 s[0:1], -1, 0
	v_writelane_b32 v251, s0, 7
	s_nop 1
	v_writelane_b32 v251, s1, 8
	s_lshl_b32 s0, s13, 6
	s_cmp_lt_i32 s13, 0
	s_mul_i32 s1, s13, 0x41
	s_cselect_b32 s0, s1, s0
	s_add_i32 s0, s0, s12
	s_ashr_i32 s1, s0, 31
	s_lshr_b32 s1, s1, 28
	s_add_i32 s1, s0, s1
	s_and_b32 s2, s1, 0xfff0
	s_sub_i32 s0, s0, s2
	s_bfe_i32 s2, s0, 0x80000
	s_bfe_u32 s2, s2, 0x2000d
	s_add_i32 s2, s0, s2
	s_and_b32 s3, s2, 0xfc
	s_sub_i32 s0, s0, s3
	s_ashr_i32 s1, s1, 4
	s_bfe_i32 s2, s2, 0x80000
	s_lshl_b32 s1, s1, 2
	s_sext_i32_i16 s2, s2
	s_sext_i32_i8 s0, s0
	v_writelane_b32 v251, s12, 9
	s_add_i32 s4, s1, s0
	s_ashr_i32 s0, s2, 2
	v_writelane_b32 v251, s0, 10
	s_lshr_b32 s0, s2, 2
	s_bfe_i64 s[0:1], s[0:1], 0x100000
	s_lshl_b64 s[0:1], s[0:1], 19
	v_writelane_b32 v251, s0, 11
	s_ashr_i32 s5, s4, 31
	s_nop 0
	v_writelane_b32 v251, s1, 12
	v_writelane_b32 v251, s13, 13
	s_lshr_b32 s0, s13, 31
	v_writelane_b32 v251, s0, 14
	s_mov_b32 s0, s4
	v_writelane_b32 v251, s0, 15
	s_nop 1
	v_writelane_b32 v251, s1, 16
	s_lshl_b64 s[0:1], s[4:5], 19
	s_add_u32 s2, s10, s0
	v_writelane_b32 v251, s10, 17
	s_mul_i32 s0, s81, s80
	s_mul_i32 s0, s0, s33
	v_writelane_b32 v251, s11, 18
	s_addc_u32 s3, s11, s1
	v_writelane_b32 v251, s0, 19
	s_add_u32 s0, s2, 0x40000
	v_writelane_b32 v251, s2, 20
	s_addc_u32 s1, s3, 0
	s_nop 0
	v_writelane_b32 v251, s3, 21
	v_writelane_b32 v251, s0, 22
	s_nop 1
	v_writelane_b32 v251, s1, 23
	s_add_u32 s0, s94, 0xea00040
	s_addc_u32 s1, s95, 0
	v_writelane_b32 v251, s0, 24
	s_add_i32 s2, 0, 0x25fc0
	s_nop 0
	v_writelane_b32 v251, s1, 25
	v_writelane_b32 v251, s2, 26
	s_add_i32 s2, 0, 0x25fc4
	v_writelane_b32 v251, s2, 27
	v_writelane_b32 v251, s68, 28
	v_writelane_b32 v251, s72, 29
	s_mov_b32 s1, 0
	s_mov_b32 s0, s1
	v_writelane_b32 v251, s73, 30
	v_writelane_b32 v251, s74, 31
	v_writelane_b32 v251, s75, 32
	v_writelane_b32 v251, s76, 33
	v_writelane_b32 v251, s77, 34
	v_writelane_b32 v251, s78, 35
	v_writelane_b32 v251, s79, 36
	v_writelane_b32 v251, s92, 37
	s_mov_b64 s[2:3], 0x80
	s_nop 0
	v_writelane_b32 v251, s93, 38
	v_writelane_b32 v251, s94, 39
	v_writelane_b32 v251, s95, 40
	v_writelane_b32 v251, s80, 41
	s_nop 1
	v_writelane_b32 v251, s81, 42
	v_writelane_b32 v251, s70, 43
	s_nop 1
	v_writelane_b32 v251, s71, 44
	v_writelane_b32 v251, s88, 45
	s_nop 1
	v_writelane_b32 v251, s89, 46
	v_writelane_b32 v251, s82, 47
	s_nop 1
	v_writelane_b32 v251, s83, 48
	v_writelane_b32 v251, s91, 49
	v_readlane_b32 s96, v252, 25
	v_readlane_b32 s97, v252, 26
	s_add_u32 s96, s96, 0x3600
	s_addc_u32 s97, s97, 0
	v_mbcnt_lo_u32_b32 v248, -1, 0
	v_mbcnt_hi_u32_b32 v248, -1, v248
	v_and_b32_e32 v248, 7, v248
	v_lshlrev_b32_e32 v248, 2, v248
	global_load_dword v249, v248, s[96:97] sc1
	global_load_dword v248, v248, s[96:97] offset:32 sc1
	s_waitcnt vmcnt(0)
	v_add_u32_e32 v248, v248, v249
	v_cmp_ne_u32_e32 vcc, 17, v248
	s_cmp_lg_u64 vcc, 0
	s_cselect_b32 s96, 1, 0
	v_writelane_b32 v250, s96, 63
	s_nop 0
	s_branch .LBB0_281

; __device__ __forceinline__ unsigned xb_add(unsigned* p, unsigned v) { return __hip_atomic_fetch_add(p, v, __ATOMIC_RELAXED, __HIP_MEMORY_SCOPE_AGENT); }
; __device__ __forceinline__ void xcd_barrier(const XcdBarrier& b) {
;     ...
;         const unsigned old = xb_add(&bar[XB_XSUB(b.x)], 1u);
;         const unsigned gen = old / nloc;
;         if (old + 1u == (gen + 1u) * nloc) {
;             __builtin_amdgcn_fence(__ATOMIC_RELEASE, "agent");
;             asm volatile("s_waitcnt vmcnt(0)" ::: "memory");
;             const unsigned og = xb_add(&bar[XB_TOP], 1u);
.LBB0_373:
	s_andn2_saveexec_b64 s[6:7], s[6:7]
	s_cbranch_execz .LBB0_393
	s_mov_b64 s[6:7], exec
	v_readlane_b32 s96, v250, 63
	s_cmp_eq_u32 s96, 0
	s_cbranch_scc1 .Lxl_0
	buffer_wbl2 sc1
	s_waitcnt lgkmcnt(0)
	s_waitcnt vmcnt(0)
	v_mbcnt_lo_u32_b32 v1, s6, 0
	v_mbcnt_hi_u32_b32 v1, s7, v1
	v_cmp_eq_u32_e32 vcc, 0, v1
	s_and_saveexec_b64 s[8:9], vcc
	s_cbranch_execz .LBB0_376
	s_bcnt1_i32_b64 s1, s[6:7]
	v_readlane_b32 s6, v253, 31
	v_mov_b32_e32 v2, s1
	v_readlane_b32 s7, v253, 32
	s_nop 4
	global_atomic_add v2, v113, v2, s[6:7] sc0

; __device__ __forceinline__ unsigned xb_add(unsigned* p, unsigned v) { return __hip_atomic_fetch_add(p, v, __ATOMIC_RELAXED, __HIP_MEMORY_SCOPE_AGENT); }
; __device__ __forceinline__ void xcd_barrier(const XcdBarrier& b) {
;     ...
;             __builtin_amdgcn_fence(__ATOMIC_ACQUIRE, "agent");
;             xb_add(&bar[XB_XGEN(b.x)], 1u);
;             asm volatile("s_waitcnt vmcnt(0)" ::: "memory");
.Lxl_0:
	s_mov_b64 s[6:7], exec
	v_mbcnt_lo_u32_b32 v0, s6, 0
	v_mbcnt_hi_u32_b32 v0, s7, v0
	v_cmp_eq_u32_e32 vcc, 0, v0
	s_waitcnt vmcnt(0)
	buffer_inv sc1
	s_and_saveexec_b64 s[8:9], vcc
	s_cbranch_execz .LBB0_392
	s_bcnt1_i32_b64 s1, s[6:7]
	v_readlane_b32 s6, v253, 29
	v_mov_b32_e32 v0, s1
	v_readlane_b32 s7, v253, 30
	s_nop 4
	global_atomic_add v113, v0, s[6:7]

; __device__ __forceinline__ unsigned xb_add(unsigned* p, unsigned v) { return __hip_atomic_fetch_add(p, v, __ATOMIC_RELAXED, __HIP_MEMORY_SCOPE_AGENT); }
; __device__ __forceinline__ void xcd_barrier(const XcdBarrier& b) {
;     ...
;         const unsigned old = xb_add(&bar[XB_XSUB(b.x)], 1u);
;         const unsigned gen = old / nloc;
;         if (old + 1u == (gen + 1u) * nloc) {
;             __builtin_amdgcn_fence(__ATOMIC_RELEASE, "agent");
;             asm volatile("s_waitcnt vmcnt(0)" ::: "memory");
;             const unsigned og = xb_add(&bar[XB_TOP], 1u);
; __global__ void __launch_bounds__(512, 2) mega_fwd(Params p) {
;     ...
;         xcd_barrier(bar);
.LBB0_554:
	s_andn2_saveexec_b64 s[4:5], s[4:5]
	s_cbranch_execz .LBB0_574
	s_mov_b64 s[4:5], exec
	v_readlane_b32 s96, v250, 63
	s_cmp_eq_u32 s96, 0
	s_cbranch_scc1 .Lxl_1
	buffer_wbl2 sc1
	s_waitcnt lgkmcnt(0)
	s_waitcnt vmcnt(0)
	v_mbcnt_lo_u32_b32 v1, s4, 0
	v_mbcnt_hi_u32_b32 v1, s5, v1
	v_cmp_eq_u32_e32 vcc, 0, v1
	s_and_saveexec_b64 s[6:7], vcc
	s_cbranch_execz .LBB0_557
	s_bcnt1_i32_b64 s4, s[4:5]
	v_mov_b32_e32 v2, s4
	v_readlane_b32 s4, v253, 31
	v_readlane_b32 s5, v253, 32
	s_nop 4
	global_atomic_add v2, v113, v2, s[4:5] sc0

; __device__ __forceinline__ unsigned xb_add(unsigned* p, unsigned v) { return __hip_atomic_fetch_add(p, v, __ATOMIC_RELAXED, __HIP_MEMORY_SCOPE_AGENT); }
; __device__ __forceinline__ void xcd_barrier(const XcdBarrier& b) {
;     ...
;             __builtin_amdgcn_fence(__ATOMIC_ACQUIRE, "agent");
;             xb_add(&bar[XB_XGEN(b.x)], 1u);
;             asm volatile("s_waitcnt vmcnt(0)" ::: "memory");
.Lxl_1:
	s_mov_b64 s[4:5], exec
	v_mbcnt_lo_u32_b32 v0, s4, 0
	v_mbcnt_hi_u32_b32 v0, s5, v0
	v_cmp_eq_u32_e32 vcc, 0, v0
	s_waitcnt vmcnt(0)
	buffer_inv sc1
	s_and_saveexec_b64 s[6:7], vcc
	s_cbranch_execz .LBB0_573
	s_bcnt1_i32_b64 s4, s[4:5]
	v_mov_b32_e32 v0, s4
	v_readlane_b32 s4, v253, 29
	v_readlane_b32 s5, v253, 30
	s_nop 4
	global_atomic_add v113, v0, s[4:5]

; __device__ __forceinline__ unsigned xb_add(unsigned* p, unsigned v) { return __hip_atomic_fetch_add(p, v, __ATOMIC_RELAXED, __HIP_MEMORY_SCOPE_AGENT); }
; __device__ __forceinline__ void xcd_barrier(const XcdBarrier& b) {
;     ...
;             __builtin_amdgcn_fence(__ATOMIC_ACQUIRE, "agent");
;             xb_add(&bar[XB_XGEN(b.x)], 1u);
;             asm volatile("s_waitcnt vmcnt(0)" ::: "memory");
; __global__ void __launch_bounds__(512, 2) mega_fwd(Params p) {
;     ...
;         if (layer < 3) xcd_barrier(bar);
.Lxl_2:
	s_mov_b64 s[4:5], exec
	v_mbcnt_lo_u32_b32 v0, s4, 0
	v_mbcnt_hi_u32_b32 v0, s5, v0
	v_cmp_eq_u32_e32 vcc, 0, v0
	s_waitcnt vmcnt(0)
	buffer_inv sc1
	s_and_saveexec_b64 s[6:7], vcc
	s_cbranch_execz .LBB0_278
	s_bcnt1_i32_b64 s4, s[4:5]
	v_mov_b32_e32 v0, s4
	v_readlane_b32 s4, v253, 29
	v_readlane_b32 s5, v253, 30
	s_nop 4
	global_atomic_add v113, v0, s[4:5]
	s_branch .LBB0_278
